# gdn scan producer: the 18 tile loads use scalar workspace base + 32-bit per-thread offsets (one add per load per chunk) instead of 64-bit VGPR address arithmetic
# speedup vs baseline: 1.0055x; 1.0055x over previous
; __device__ __forceinline__ void gdn_scan(const Ctx& c, const Params& p, int e) {
;     ...
;         if (producer) {
;             int pt_ = ptid; asm volatile("" : "+v"(pt_));
;             u32x4 tq[4], tk[4], tw[4], tu[4], tqk[2];
;             const int prow = pt_ >> 4, pc8 = (pt_ & 15) * 8;
;             const int qrow = pt_ >> 3, qc8 = (pt_ & 7) * 8;
;             GDN_LOAD_TILES(0); GDN_STORE_TILES();
.LBB0_530:
	s_and_b64 vcc, exec, s[2:3]
	s_cbranch_vccz .LBB0_521
	s_mul_hi_i32 s2, s20, 0x2aaaaaab
	s_lshr_b32 s3, s2, 31
	s_add_i32 s2, s2, s3
	s_mul_i32 s3, s2, 6
	s_sub_i32 s3, s20, s3
	s_waitcnt vmcnt(0)
	v_mov_b32_e32 v97, v165
	s_lshl_b32 s4, s2, 13
	v_ashrrev_i32_e32 v64, 4, v97
	v_lshlrev_b32_e32 v1, 3, v97
	s_lshl_b32 s2, s3, 7
	s_waitcnt lgkmcnt(0)
	v_and_b32_e32 v12, 0x78, v1
	s_ashr_i32 s5, s4, 31
	v_ashrrev_i32_e32 v65, 31, v64
	s_ashr_i32 s3, s2, 31
	v_lshl_add_u64 v[2:3], v[64:65], 0, s[4:5]
	v_or_b32_e32 v102, s2, v12
	v_mov_b32_e32 v103, s3
	s_movk_i32 s35, 0x300
	v_and_b32_e32 v66, 56, v1
	v_mad_u64_u32 v[6:7], s[20:21], v2, s35, v[102:103]
	v_add_u32_e32 v1, 0x100, v97
	v_mad_i32_i24 v7, v3, s35, v7
	v_mov_b64_e32 v[10:11], s[16:17]
	v_ashrrev_i32_e32 v106, 4, v1
	v_mad_u64_u32 v[4:5], s[20:21], v2, s69, v[10:11]
	v_lshlrev_b64 v[6:7], 1, v[6:7]
	v_ashrrev_i32_e32 v107, 31, v106
	v_mad_i32_i24 v5, v3, s69, v5
	s_lshl_b64 s[20:21], s[2:3], 1
	v_lshlrev_b32_e32 v114, 4, v97
	v_lshl_add_u64 v[68:69], s[8:9], 0, v[6:7]
	v_lshl_add_u64 v[78:79], s[6:7], 0, v[6:7]
	v_lshl_add_u64 v[6:7], v[106:107], 0, s[4:5]
	v_lshl_add_u64 v[8:9], v[4:5], 0, s[20:21]
	v_lshlrev_b32_e32 v104, 1, v12
	v_mov_b32_e32 v105, v0
	v_and_b32_e32 v4, 0x80, v114
	v_mov_b32_e32 v5, v0
	v_mad_u64_u32 v[32:33], s[2:3], v6, s69, v[10:11]
	v_lshl_add_u64 v[14:15], v[8:9], 0, v[104:105]
	v_lshl_add_u64 v[12:13], v[8:9], 0, v[4:5]
	v_lshlrev_b32_e32 v8, 1, v66
	v_mov_b32_e32 v9, v0
	v_mad_i32_i24 v33, v7, s69, v33
	v_lshl_add_u64 v[12:13], v[12:13], 0, v[8:9]
	v_lshl_add_u64 v[32:33], v[32:33], 0, s[20:21]
	global_load_dwordx4 v[16:19], v[14:15], off offset:1536
	global_load_dwordx4 v[20:23], v[12:13], off offset:3072
	v_add_co_u32_e32 v12, vcc, s47, v14
	v_lshl_add_u64 v[32:33], v[32:33], 0, v[4:5]
	s_nop 0
	v_addc_co_u32_e32 v13, vcc, 0, v15, vcc
	v_lshl_add_u64 v[36:37], v[32:33], 0, v[8:9]
	s_movk_i32 s0, 0x6000
	global_load_dwordx4 v[24:27], v[68:69], off
	global_load_dwordx4 v[28:31], v[78:79], off
	global_load_dwordx4 v[32:35], v[12:13], off offset:2048
	s_nop 0
	global_load_dwordx4 v[36:39], v[36:37], off offset:3072
	v_add_co_u32_e32 v12, vcc, s0, v68
	s_mov_b32 s39, 0x3c000
	s_nop 0
	v_addc_co_u32_e32 v13, vcc, 0, v69, vcc
	v_add_co_u32_e32 v44, vcc, s0, v78
	v_add_u32_e32 v94, 0x200, v97
	s_nop 0
	v_addc_co_u32_e32 v45, vcc, 0, v79, vcc
	v_add_co_u32_e32 v48, vcc, s39, v14
	v_add_u32_e32 v95, 0x300, v97
	s_nop 0
	v_addc_co_u32_e32 v49, vcc, 0, v15, vcc
	v_add_co_u32_e32 v56, vcc, s62, v68
	v_ashrrev_i32_e32 v108, 4, v94
	s_nop 0
	v_addc_co_u32_e32 v57, vcc, 0, v69, vcc
	v_add_co_u32_e32 v60, vcc, s62, v78
	s_mov_b32 s42, 0x5a000
	s_nop 0
	v_addc_co_u32_e32 v61, vcc, 0, v79, vcc
	v_ashrrev_i32_e32 v110, 4, v95
	v_ashrrev_i32_e32 v109, 31, v108
	v_add_co_u32_e32 v70, vcc, s42, v14
	v_ashrrev_i32_e32 v111, 31, v110
	global_load_dwordx4 v[40:43], v[12:13], off
	s_nop 0
	global_load_dwordx4 v[44:47], v[44:45], off
	v_lshl_add_u64 v[12:13], v[108:109], 0, s[4:5]
	v_addc_co_u32_e32 v71, vcc, 0, v15, vcc
	v_lshl_add_u64 v[14:15], v[110:111], 0, s[4:5]
	v_mad_u64_u32 v[50:51], s[2:3], v12, s69, v[10:11]
	v_mad_u64_u32 v[72:73], s[2:3], v14, s69, v[10:11]
	v_mad_i32_i24 v51, v13, s69, v51
	v_mad_i32_i24 v73, v15, s69, v73
	v_add_co_u32_e32 v68, vcc, s63, v68
	v_lshl_add_u64 v[50:51], v[50:51], 0, s[20:21]
	v_lshl_add_u64 v[72:73], v[72:73], 0, s[20:21]
	v_addc_co_u32_e32 v69, vcc, 0, v69, vcc
	v_lshl_add_u64 v[50:51], v[50:51], 0, v[4:5]
	v_lshl_add_u64 v[72:73], v[72:73], 0, v[4:5]
	v_add_co_u32_e32 v82, vcc, s63, v78
	v_lshl_add_u64 v[52:53], v[50:51], 0, v[8:9]
	v_lshl_add_u64 v[74:75], v[72:73], 0, v[8:9]
	v_addc_co_u32_e32 v83, vcc, 0, v79, vcc
	global_load_dwordx4 v[48:51], v[48:49], off offset:2560
	s_nop 0
	global_load_dwordx4 v[52:55], v[52:53], off offset:3072
	s_nop 0
	global_load_dwordx4 v[56:59], v[56:57], off
	s_nop 0
	global_load_dwordx4 v[60:63], v[60:61], off
	s_nop 0
	global_load_dwordx4 v[70:73], v[70:71], off offset:3072
	s_nop 0
	global_load_dwordx4 v[74:77], v[74:75], off offset:3072
	s_nop 0
	global_load_dwordx4 v[78:81], v[68:69], off
	s_nop 0
	global_load_dwordx4 v[82:85], v[82:83], off
	v_ashrrev_i32_e32 v68, 3, v97
	v_ashrrev_i32_e32 v69, 31, v68
	v_lshl_add_u64 v[112:113], v[68:69], 0, s[4:5]
	v_mad_u64_u32 v[86:87], s[2:3], v112, s69, v[10:11]
	v_mad_i32_i24 v87, v113, s69, v87
	v_lshl_add_u64 v[86:87], v[86:87], 0, s[20:21]
	v_lshl_add_u64 v[86:87], v[86:87], 0, v[8:9]
	s_movk_i32 s5, 0x1000
	v_add_co_u32_e32 v88, vcc, s5, v86
	s_mov_b32 s44, 0x3d000
	s_nop 0
	v_addc_co_u32_e32 v89, vcc, 0, v87, vcc
	v_add_co_u32_e32 v90, vcc, s44, v86
	v_mul_lo_u32 v67, v64, s36
	s_nop 0
	v_addc_co_u32_e32 v91, vcc, 0, v87, vcc
	global_load_dwordx4 v[86:89], v[88:89], off offset:512
	s_nop 0
	global_load_dwordx4 v[98:101], v[90:91], off offset:1536
	v_add3_u32 v91, s80, v104, v67
	s_waitcnt vmcnt(0) lgkmcnt(0)
	ds_write_b128 v91, v[16:19]
	ds_write_b128 v91, v[24:27] offset:17408
	ds_write_b128 v91, v[28:31] offset:34816
	s_movk_i32 s2, 0x90
	v_lshrrev_b32_e32 v116, 3, v94
	v_add_u32_e32 v96, s80, v8
	v_mul_lo_u32 v116, v116, s2
	v_ashrrev_i32_e32 v1, 3, v1
	v_add_u32_e32 v94, v96, v116
	v_lshrrev_b32_e32 v116, 3, v95
	v_mul_lo_u32 v90, v68, s2
	v_mul_lo_u32 v67, v1, s2
	v_mul_lo_u32 v116, v116, s2
	s_or_b32 s2, s4, 64
	v_add_u32_e32 v95, v96, v116
	v_add_u32_e32 v116, s24, v8
	s_ashr_i32 s3, s2, 31
	v_add_u32_e32 v92, v96, v90
	v_add_u32_e32 v93, v96, v67
	v_add_u32_e32 v96, v116, v90
	v_lshl_add_u64 v[116:117], v[64:65], 0, s[2:3]
	v_mad_u64_u32 v[118:119], s[40:41], v116, s69, v[10:11]
	v_mad_u64_u32 v[120:121], s[40:41], v116, s35, v[102:103]
	v_mad_i32_i24 v119, v117, s69, v119
	v_mad_i32_i24 v121, v117, s35, v121
	v_lshl_add_u64 v[116:117], v[118:119], 0, s[20:21]
	v_lshl_add_u64 v[64:65], v[116:117], 0, v[104:105]
	ds_write_b128 v92, v[20:23] offset:52224
	ds_write_b128 v91, v[32:35] offset:4352
	ds_write_b128 v91, v[40:43] offset:21760
	ds_write_b128 v91, v[44:47] offset:39168
	v_lshlrev_b64 v[120:121], 1, v[120:121]
	v_add_co_u32_e32 v132, vcc, s47, v64
	ds_write_b128 v93, v[36:39] offset:52224
	ds_write_b128 v91, v[48:51] offset:8704
	ds_write_b128 v91, v[56:59] offset:26112
	ds_write_b128 v91, v[60:63] offset:43520
	ds_write_b128 v94, v[52:55] offset:52224
	ds_write_b128 v91, v[70:73] offset:13056
	ds_write_b128 v91, v[78:81] offset:30464
	ds_write_b128 v91, v[82:85] offset:47872
	v_lshl_add_u64 v[224:225], s[8:9], 0, v[120:121]
	v_addc_co_u32_e32 v133, vcc, 0, v65, vcc
	v_add_co_u32_e32 v136, vcc, s0, v224
	v_lshl_add_u64 v[226:227], s[6:7], 0, v[120:121]
	s_nop 0
	v_addc_co_u32_e32 v137, vcc, 0, v225, vcc
	v_add_co_u32_e32 v140, vcc, s0, v226
	v_lshl_add_u64 v[134:135], v[106:107], 0, s[2:3]
	s_nop 0
	v_addc_co_u32_e32 v141, vcc, 0, v227, vcc
	v_add_co_u32_e32 v204, vcc, s39, v64
	v_lshl_add_u64 v[206:207], v[108:109], 0, s[2:3]
	s_nop 0
	v_addc_co_u32_e32 v205, vcc, 0, v65, vcc
	v_add_co_u32_e32 v208, vcc, s62, v224
	v_lshl_add_u64 v[220:221], v[110:111], 0, s[2:3]
	v_mad_u64_u32 v[200:201], s[40:41], v134, s69, v[10:11]
	v_mad_u64_u32 v[216:217], s[40:41], v206, s69, v[10:11]
	v_addc_co_u32_e32 v209, vcc, 0, v225, vcc
	v_mad_u64_u32 v[222:223], s[40:41], v220, s69, v[10:11]
	ds_write_b128 v95, v[74:77] offset:52224
	ds_write_b128 v96, v[86:89]
	ds_write_b128 v96, v[98:101] offset:4608
	v_lshl_add_u64 v[116:117], v[116:117], 0, v[4:5]
	v_mad_i32_i24 v201, v135, s69, v201
	v_mad_i32_i24 v217, v207, s69, v217
	v_add_co_u32_e32 v212, vcc, s62, v226
	v_mad_i32_i24 v223, v221, s69, v223
	v_lshl_add_u64 v[128:129], v[116:117], 0, v[8:9]
	v_lshl_add_u64 v[134:135], v[200:201], 0, s[20:21]
	v_lshl_add_u64 v[206:207], v[216:217], 0, s[20:21]
	v_addc_co_u32_e32 v213, vcc, 0, v227, vcc
	v_lshl_add_u64 v[220:221], v[222:223], 0, s[20:21]
	global_load_dwordx4 v[116:119], v[64:65], off offset:1536
	s_nop 0
	global_load_dwordx4 v[128:131], v[128:129], off offset:3072
	v_lshl_add_u64 v[134:135], v[134:135], 0, v[4:5]
	v_lshl_add_u64 v[206:207], v[206:207], 0, v[4:5]
	v_add_co_u32_e32 v64, vcc, s42, v64
	v_lshl_add_u64 v[220:221], v[220:221], 0, v[4:5]
	v_lshl_add_u64 v[200:201], v[134:135], 0, v[8:9]
	v_lshl_add_u64 v[216:217], v[206:207], 0, v[8:9]
	v_addc_co_u32_e32 v65, vcc, 0, v65, vcc
	v_lshl_add_u64 v[232:233], v[220:221], 0, v[8:9]
	global_load_dwordx4 v[120:123], v[224:225], off
	global_load_dwordx4 v[124:127], v[226:227], off
	s_nop 0
	global_load_dwordx4 v[132:135], v[132:133], off offset:2048
	s_nop 0
	global_load_dwordx4 v[200:203], v[200:201], off offset:3072
	s_nop 0
	global_load_dwordx4 v[136:139], v[136:137], off
	s_nop 0
	global_load_dwordx4 v[140:143], v[140:141], off
	s_nop 0
	global_load_dwordx4 v[204:207], v[204:205], off offset:2560
	s_nop 0
	global_load_dwordx4 v[216:219], v[216:217], off offset:3072
	s_nop 0
	global_load_dwordx4 v[208:211], v[208:209], off
	s_nop 0
	global_load_dwordx4 v[212:215], v[212:213], off
	s_nop 0
	global_load_dwordx4 v[220:223], v[64:65], off offset:3072
	s_nop 0
	global_load_dwordx4 v[232:235], v[232:233], off offset:3072
	v_add_co_u32_e32 v64, vcc, s63, v224
	s_nop 1
	v_addc_co_u32_e32 v65, vcc, 0, v225, vcc
	v_add_co_u32_e32 v228, vcc, s63, v226
	s_nop 1
	v_addc_co_u32_e32 v229, vcc, 0, v227, vcc
	global_load_dwordx4 v[224:227], v[64:65], off
	s_nop 0
	global_load_dwordx4 v[228:231], v[228:229], off
	v_lshl_add_u64 v[64:65], v[68:69], 0, s[2:3]
	v_mad_u64_u32 v[10:11], s[2:3], v64, s69, v[10:11]
	v_mad_i32_i24 v11, v65, s69, v11
	v_lshl_add_u64 v[10:11], v[10:11], 0, s[20:21]
	v_lshl_add_u64 v[10:11], v[10:11], 0, v[8:9]
	v_add_co_u32_e32 v64, vcc, s5, v10
	s_add_u32 s3, s74, s20
	s_nop 0
	v_addc_co_u32_e32 v65, vcc, 0, v11, vcc
	v_add_co_u32_e32 v10, vcc, s44, v10
	s_addc_u32 s5, s75, s21
	s_nop 0
	v_addc_co_u32_e32 v11, vcc, 0, v11, vcc
	global_load_dwordx4 v[236:239], v[64:65], off offset:512
	global_load_dwordx4 v[240:243], v[10:11], off offset:1536
	s_lshl_b32 s35, s34, 1
	s_add_u32 s40, s3, s35
	s_addc_u32 s41, s5, 0
	v_add_u32_e32 v69, s25, v8
	v_lshl_add_u64 v[70:71], s[40:41], 0, v[8:9]
	v_and_b32_e32 v8, 7, v97
	v_lshlrev_b32_e32 v8, 4, v8
	v_mad_u64_u32 v[10:11], s[40:41], v112, s69, v[8:9]
	v_mad_i32_i24 v11, v113, s69, v11
	v_lshl_add_u64 v[76:77], s[22:23], 0, v[10:11]
	v_mad_u64_u32 v[10:11], s[40:41], v14, s69, v[4:5]
	v_mad_i32_i24 v11, v15, s69, v11
	v_lshl_add_u64 v[10:11], v[10:11], 0, v[8:9]
	v_lshl_add_u64 v[78:79], s[18:19], 0, v[10:11]
	v_mad_u64_u32 v[10:11], s[40:41], v12, s69, v[4:5]
	v_mad_i32_i24 v11, v13, s69, v11
	v_lshl_add_u64 v[10:11], v[10:11], 0, v[8:9]
	v_lshl_add_u64 v[80:81], s[18:19], 0, v[10:11]
	v_mad_u64_u32 v[10:11], s[40:41], v6, s69, v[4:5]
	v_mad_i32_i24 v11, v7, s69, v11
	v_mad_u64_u32 v[4:5], s[40:41], v2, s69, v[4:5]
	v_lshl_add_u64 v[6:7], v[10:11], 0, v[8:9]
	v_mad_i32_i24 v5, v3, s69, v5
	v_lshl_add_u64 v[82:83], s[18:19], 0, v[6:7]
	v_and_b32_e32 v6, 0xf0, v114
	v_mov_b32_e32 v7, v0
	v_lshl_add_u64 v[4:5], v[4:5], 0, v[8:9]
	v_mad_u64_u32 v[10:11], s[40:41], v2, s69, v[6:7]
	v_lshl_add_u64 v[86:87], s[18:19], 0, v[4:5]
	v_mad_u64_u32 v[4:5], s[40:41], v2, s50, 0
	v_mad_i32_i24 v11, v3, s69, v11
	v_mad_i32_i24 v3, v3, s50, v5
	v_or_b32_e32 v2, v4, v6
	s_mov_b32 s2, 0
	v_add_u32_e32 v72, s4, v1
	v_add_u32_e32 v74, s4, v68
	v_lshl_add_u64 v[84:85], s[22:23], 0, v[10:11]
	v_lshl_add_u64 v[88:89], s[22:23], 0, v[2:3]
	s_mov_b32 s2, -1
	v_subrev_u32_e32 v72, 64, v72
	v_subrev_u32_e32 v74, 64, v74
	s_mov_b32 s98, 0xff00ff
	s_mov_b32 s99, 0xff00ff00
	s_cmp_eq_u32 s34, 0
	s_cselect_b32 s98, s98, s99
	s_mov_b32 s99, s98
	v_lshl_add_u64 v[50:51], v[84:85], 0, s[20:21]
	v_add_co_u32_e32 v2, vcc, 0x81f1000, v50
	v_lshl_add_u64 v[62:63], v[88:89], 0, s[20:21]
	s_nop 0
	v_addc_co_u32_e32 v3, vcc, 0, v51, vcc
	v_add_co_u32_e32 v10, vcc, 0x1a230000, v62
	s_nop 0
	v_addc_co_u32_e32 v11, vcc, 0, v63, vcc
	v_add_co_u32_e32 v14, vcc, 0x17230000, v62
	v_subrev_u32_e32 v244, s22, v2
	s_nop 0
	v_addc_co_u32_e32 v15, vcc, 0, v63, vcc
	v_add_co_u32_e32 v18, vcc, 0x820f000, v50
	v_subrev_u32_e32 v245, s22, v10
	s_nop 0
	v_addc_co_u32_e32 v19, vcc, 0, v51, vcc
	v_add_co_u32_e32 v26, vcc, 0x1a236000, v62
	v_lshl_add_u64 v[6:7], v[86:87], 0, s[20:21]
	s_nop 0
	v_addc_co_u32_e32 v27, vcc, 0, v63, vcc
	v_add_co_u32_e32 v30, vcc, 0x17236000, v62
	v_subrev_u32_e32 v246, s22, v14
	s_nop 0
	v_addc_co_u32_e32 v31, vcc, 0, v63, vcc
	v_add_co_u32_e32 v34, vcc, 0x822d000, v50
	v_subrev_u32_e32 v247, s22, v6
	s_nop 0
	v_addc_co_u32_e32 v35, vcc, 0, v51, vcc
	v_add_co_u32_e32 v42, vcc, 0x1a23c000, v62
	v_subrev_u32_e32 v248, s22, v18
	s_nop 0
	v_addc_co_u32_e32 v43, vcc, 0, v63, vcc
	v_subrev_u32_e32 v249, s22, v26
	v_add_co_u32_e32 v46, vcc, 0x1723c000, v62
	v_lshl_add_u64 v[22:23], v[82:83], 0, s[20:21]
	v_subrev_u32_e32 v250, s22, v30
	v_addc_co_u32_e32 v47, vcc, 0, v63, vcc
	v_subrev_u32_e32 v251, s22, v22
	v_add_co_u32_e32 v50, vcc, 0x824b000, v50
	v_subrev_u32_e32 v252, s22, v34
	s_nop 0
	v_addc_co_u32_e32 v51, vcc, 0, v51, vcc
	v_subrev_u32_e32 v253, s22, v42
	v_add_co_u32_e32 v58, vcc, 0x1a242000, v62
	v_lshl_add_u64 v[38:39], v[80:81], 0, s[20:21]
	v_subrev_u32_e32 v112, s22, v46
	v_addc_co_u32_e32 v59, vcc, 0, v63, vcc
	v_subrev_u32_e32 v113, s22, v38
	v_add_co_u32_e32 v62, vcc, 0x17242000, v62
	v_subrev_u32_e32 v114, s22, v50
	s_nop 0
	v_addc_co_u32_e32 v63, vcc, 0, v63, vcc
	v_lshl_add_u64 v[102:103], v[76:77], 0, s[20:21]
	v_subrev_u32_e32 v115, s22, v58
	v_add_co_u32_e32 v98, vcc, 0x81f2000, v102
	v_lshl_add_u64 v[54:55], v[78:79], 0, s[20:21]
	v_subrev_u32_e32 v106, s22, v62
	v_addc_co_u32_e32 v99, vcc, 0, v103, vcc
	v_subrev_u32_e32 v107, s22, v54
	v_add_co_u32_e32 v102, vcc, 0x822e000, v102
	v_subrev_u32_e32 v108, s22, v98
	s_nop 0
	v_addc_co_u32_e32 v103, vcc, 0, v103, vcc
	v_subrev_u32_e32 v109, s22, v102
	v_mov_b32_e32 v76, v106
	v_mov_b32_e32 v77, v107
	v_mov_b32_e32 v78, v108
	v_mov_b32_e32 v79, v109

; #define LDS_BARRIER() do { asm volatile("s_waitcnt lgkmcnt(0)" ::: "memory"); __builtin_amdgcn_s_barrier(); asm volatile("" ::: "memory"); } while (0)
; #define GDN_STORE_O(nn) do { const LAS bf16_t* ob_ = OTb + ((nn) & 1) * 4608; _Pragma("unroll") for (int k_ = 0; k_ < 2; ++k_) { const int vi_ = pt_ + 256 * k_, row_ = vi_ >> 3, c8_ = (vi_ & 7) * 8; \
;             *(u32x4*)(Y + (size_t)(b * T_ + 64 * (nn) + row_) * D_ + 256 + h * 128 + 64 * dvh + c8_) = *(const LAS u32x4*)(ob_ + row_ * 72 + c8_); } } while (0)
; __device__ __forceinline__ void gdn_scan(const Ctx& c, const Params& p, int e) {
;     ...
;             for (int n = 0; n < 128; ++n) {
;                 LDS_BARRIER();
;                 if (n + 1 < 128) GDN_LOAD_TILES(n + 1);
;                 if (n >= 1) GDN_STORE_O(n - 1);
;                 LDS_BARRIER();
;                 if (n + 1 < 128) GDN_STORE_TILES();
.Lgp_e_nost:
	s_cmpk_eq_i32 s2, 0x7d
	s_cbranch_scc1 .Lgp_e_nold
	global_load_dwordx4 v[2:5], v244, s[22:23] offset:1536
	global_load_dwordx4 v[10:13], v245, s[22:23]
	s_mov_b64 exec, s[98:99]
	global_load_dwordx4 v[14:17], v246, s[22:23]
	s_mov_b64 exec, -1
	global_load_dwordx4 v[6:9], v247, s[22:23]
	global_load_dwordx4 v[18:21], v248, s[22:23] offset:2048
	global_load_dwordx4 v[26:29], v249, s[22:23]
	s_mov_b64 exec, s[98:99]
	global_load_dwordx4 v[30:33], v250, s[22:23]
	s_mov_b64 exec, -1
	global_load_dwordx4 v[22:25], v251, s[22:23]
	global_load_dwordx4 v[34:37], v252, s[22:23] offset:2560
	global_load_dwordx4 v[42:45], v253, s[22:23]
	s_mov_b64 exec, s[98:99]
	global_load_dwordx4 v[46:49], v112, s[22:23]
	s_mov_b64 exec, -1
	global_load_dwordx4 v[38:41], v113, s[22:23]
	global_load_dwordx4 v[50:53], v114, s[22:23] offset:3072
	global_load_dwordx4 v[58:61], v115, s[22:23]
	s_mov_b64 exec, s[98:99]
	global_load_dwordx4 v[62:65], v76, s[22:23]
	s_mov_b64 exec, -1
	global_load_dwordx4 v[54:57], v77, s[22:23]
	global_load_dwordx4 v[98:101], v78, s[22:23] offset:512
	global_load_dwordx4 v[102:105], v79, s[22:23] offset:1536
	v_add_u32_e32 v244, 0x78800, v244
	v_add_u32_e32 v245, 0x18000, v245
	v_add_u32_e32 v246, 0x18000, v246
	v_add_u32_e32 v247, 0x78800, v247
	v_add_u32_e32 v248, 0x78800, v248
	v_add_u32_e32 v249, 0x18000, v249
	v_add_u32_e32 v250, 0x18000, v250
	v_add_u32_e32 v251, 0x78800, v251
	v_add_u32_e32 v252, 0x78800, v252
	v_add_u32_e32 v253, 0x18000, v253
	v_add_u32_e32 v112, 0x18000, v112
	v_add_u32_e32 v113, 0x78800, v113
	v_add_u32_e32 v114, 0x78800, v114
	v_add_u32_e32 v115, 0x18000, v115
	v_add_u32_e32 v76, 0x18000, v76
	v_add_u32_e32 v77, 0x78800, v77
	v_add_u32_e32 v78, 0x78800, v78
	v_add_u32_e32 v79, 0x78800, v79
.Lgp_e_nold:
	s_add_i32 s2, s2, 1
	s_waitcnt lgkmcnt(0)
	s_barrier
	s_mov_b64 s[40:41], 0x18000
	v_add_u32_e32 v72, 64, v72
	v_add_u32_e32 v74, 64, v74
	s_cmpk_eq_i32 s2, 0x7e
	s_cbranch_scc1 .Lgp_e_w0
	s_waitcnt vmcnt(18)
	s_branch .Lgp_e_wr

; #define LDS_BARRIER() do { asm volatile("s_waitcnt lgkmcnt(0)" ::: "memory"); __builtin_amdgcn_s_barrier(); asm volatile("" ::: "memory"); } while (0)
; #define GDN_STORE_O(nn) do { const LAS bf16_t* ob_ = OTb + ((nn) & 1) * 4608; _Pragma("unroll") for (int k_ = 0; k_ < 2; ++k_) { const int vi_ = pt_ + 256 * k_, row_ = vi_ >> 3, c8_ = (vi_ & 7) * 8; \
;             *(u32x4*)(Y + (size_t)(b * T_ + 64 * (nn) + row_) * D_ + 256 + h * 128 + 64 * dvh + c8_) = *(const LAS u32x4*)(ob_ + row_ * 72 + c8_); } } while (0)
; __device__ __forceinline__ void gdn_scan(const Ctx& c, const Params& p, int e) {
;     ...
;             for (int n = 0; n < 128; ++n) {
;                 LDS_BARRIER();
;                 if (n + 1 < 128) GDN_LOAD_TILES(n + 1);
;                 if (n >= 1) GDN_STORE_O(n - 1);
;                 LDS_BARRIER();
;                 if (n + 1 < 128) GDN_STORE_TILES();
.Lgp_e_wr:
	ds_write_b128 v91, v[116:119]
	ds_write_b128 v91, v[120:123] offset:17408
	ds_write_b128 v91, v[124:127] offset:34816
	ds_write_b128 v92, v[128:131] offset:52224
	ds_write_b128 v91, v[132:135] offset:4352
	ds_write_b128 v91, v[136:139] offset:21760
	ds_write_b128 v91, v[140:143] offset:39168
	ds_write_b128 v93, v[200:203] offset:52224
	ds_write_b128 v91, v[204:207] offset:8704
	ds_write_b128 v91, v[208:211] offset:26112
	ds_write_b128 v91, v[212:215] offset:43520
	ds_write_b128 v94, v[216:219] offset:52224
	ds_write_b128 v91, v[220:223] offset:13056
	ds_write_b128 v91, v[224:227] offset:30464
	ds_write_b128 v91, v[228:231] offset:47872
	ds_write_b128 v95, v[232:235] offset:52224
	ds_write_b128 v96, v[236:239]
	ds_write_b128 v96, v[240:243] offset:4608
	s_cmpk_eq_i32 s2, 0x7e
	s_cbranch_scc1 .Lgp_done
	s_waitcnt lgkmcnt(0)
	s_barrier
	s_bitcmp1_b32 s2, 0
	s_cselect_b32 s3, 0x2400, 0
	v_add_u32_e32 v73, s3, v69
	v_add_u32_e32 v75, v73, v90
	ds_read_b128 v[106:109], v75
	v_ashrrev_i32_e32 v75, 31, v74
	v_lshlrev_b64 v[110:111], 11, v[74:75]
	v_lshl_add_u64 v[110:111], v[70:71], 0, v[110:111]
	v_add_u32_e32 v73, v73, v67
	s_waitcnt lgkmcnt(0)
	global_store_dwordx4 v[110:111], v[106:109], off offset:512
	ds_read_b128 v[106:109], v73
	v_ashrrev_i32_e32 v73, 31, v72
	v_lshlrev_b64 v[110:111], 11, v[72:73]
	v_lshl_add_u64 v[110:111], v[70:71], 0, v[110:111]
	s_waitcnt lgkmcnt(0)
	global_store_dwordx4 v[110:111], v[106:109], off offset:512
	global_load_dwordx4 v[116:119], v244, s[22:23] offset:1536
	global_load_dwordx4 v[120:123], v245, s[22:23]
	s_mov_b64 exec, s[98:99]
	global_load_dwordx4 v[124:127], v246, s[22:23]
	s_mov_b64 exec, -1
	global_load_dwordx4 v[128:131], v247, s[22:23]
	global_load_dwordx4 v[132:135], v248, s[22:23] offset:2048
	global_load_dwordx4 v[136:139], v249, s[22:23]
	s_mov_b64 exec, s[98:99]
	global_load_dwordx4 v[140:143], v250, s[22:23]
	s_mov_b64 exec, -1
	global_load_dwordx4 v[200:203], v251, s[22:23]
	global_load_dwordx4 v[204:207], v252, s[22:23] offset:2560
	global_load_dwordx4 v[208:211], v253, s[22:23]
	s_mov_b64 exec, s[98:99]
	global_load_dwordx4 v[212:215], v112, s[22:23]
	s_mov_b64 exec, -1
	global_load_dwordx4 v[216:219], v113, s[22:23]
	global_load_dwordx4 v[220:223], v114, s[22:23] offset:3072
	global_load_dwordx4 v[224:227], v115, s[22:23]
	s_mov_b64 exec, s[98:99]
	global_load_dwordx4 v[228:231], v76, s[22:23]
	s_mov_b64 exec, -1
	global_load_dwordx4 v[232:235], v77, s[22:23]
	global_load_dwordx4 v[236:239], v78, s[22:23] offset:512
	global_load_dwordx4 v[240:243], v79, s[22:23] offset:1536
	v_add_u32_e32 v244, 0x78800, v244
	v_add_u32_e32 v245, 0x18000, v245
	v_add_u32_e32 v246, 0x18000, v246
	v_add_u32_e32 v247, 0x78800, v247
	v_add_u32_e32 v248, 0x78800, v248
	v_add_u32_e32 v249, 0x18000, v249
	v_add_u32_e32 v250, 0x18000, v250
	v_add_u32_e32 v251, 0x78800, v251
	v_add_u32_e32 v252, 0x78800, v252
	v_add_u32_e32 v253, 0x18000, v253
	v_add_u32_e32 v112, 0x18000, v112
	v_add_u32_e32 v113, 0x78800, v113
	v_add_u32_e32 v114, 0x78800, v114
	v_add_u32_e32 v115, 0x18000, v115
	v_add_u32_e32 v76, 0x18000, v76
	v_add_u32_e32 v77, 0x78800, v77
	v_add_u32_e32 v78, 0x78800, v78
	v_add_u32_e32 v79, 0x78800, v79
	s_add_i32 s2, s2, 1
	s_waitcnt lgkmcnt(0)
	s_barrier
	s_mov_b64 s[40:41], 0x18000
	v_add_u32_e32 v72, 64, v72
	v_add_u32_e32 v74, 64, v74
	s_waitcnt vmcnt(18)
	ds_write_b128 v91, v[2:5]
	ds_write_b128 v91, v[10:13] offset:17408
	ds_write_b128 v91, v[14:17] offset:34816
	ds_write_b128 v92, v[6:9] offset:52224
	ds_write_b128 v91, v[18:21] offset:4352
	ds_write_b128 v91, v[26:29] offset:21760
	ds_write_b128 v91, v[30:33] offset:39168
	ds_write_b128 v93, v[22:25] offset:52224
	ds_write_b128 v91, v[34:37] offset:8704
	ds_write_b128 v91, v[42:45] offset:26112
	ds_write_b128 v91, v[46:49] offset:43520
	ds_write_b128 v94, v[38:41] offset:52224
	ds_write_b128 v91, v[50:53] offset:13056
	ds_write_b128 v91, v[58:61] offset:30464
	ds_write_b128 v91, v[62:65] offset:47872
	ds_write_b128 v95, v[54:57] offset:52224
	ds_write_b128 v96, v[98:101]
	ds_write_b128 v96, v[102:105] offset:4608
	s_branch .Lgp_even
